# grid barrier: the workgroup completing the cross-XCC count bumps every XCC generation word itself (XCC leaders no longer relay the release); on top of v126
# speedup vs baseline: 1.0004x; 1.0002x over previous
.LBB0_325:
	s_or_b64 exec, exec, s[8:9]
	s_and_saveexec_b64 s[8:9], s[12:13]
	s_cbranch_execz .LBB0_327
	v_mov_b32_e32 v2, 1
	global_atomic_add v[0:1], v2, off
	v_mov_b32_e32 v3, 0x2400
	global_atomic_add v3, v2, s[88:89]
	v_mov_b32_e32 v3, 0x2500
	global_atomic_add v3, v2, s[88:89]
	v_mov_b32_e32 v3, 0x2600
	global_atomic_add v3, v2, s[88:89]
	v_mov_b32_e32 v3, 0x2700
	global_atomic_add v3, v2, s[88:89]
	v_mov_b32_e32 v3, 0x2800
	global_atomic_add v3, v2, s[88:89]
	v_mov_b32_e32 v3, 0x2900
	global_atomic_add v3, v2, s[88:89]
	v_mov_b32_e32 v3, 0x2a00
	global_atomic_add v3, v2, s[88:89]
	v_mov_b32_e32 v3, 0x2b00
	global_atomic_add v3, v2, s[88:89]
	v_mov_b32_e32 v3, 0x2c00
	global_atomic_add v3, v2, s[88:89]
	v_mov_b32_e32 v3, 0x2d00
	global_atomic_add v3, v2, s[88:89]
	v_mov_b32_e32 v3, 0x2e00
	global_atomic_add v3, v2, s[88:89]
	v_mov_b32_e32 v3, 0x2f00
	global_atomic_add v3, v2, s[88:89]
	v_mov_b32_e32 v3, 0x3000
	global_atomic_add v3, v2, s[88:89]
	v_mov_b32_e32 v3, 0x3100
	global_atomic_add v3, v2, s[88:89]
	v_mov_b32_e32 v3, 0x3200
	global_atomic_add v3, v2, s[88:89]
	v_mov_b32_e32 v3, 0x3300
	global_atomic_add v3, v2, s[88:89]
.LBB0_327:
	s_or_b64 exec, exec, s[8:9]
	s_mov_b64 s[8:9], exec
	v_mbcnt_lo_u32_b32 v0, s8, 0
	v_mbcnt_hi_u32_b32 v0, s9, v0
	v_cmp_eq_u32_e32 vcc, 0, v0
	s_waitcnt vmcnt(0)
	buffer_inv sc1
	s_and_saveexec_b64 s[10:11], vcc
	s_cbranch_execz .LBB0_329
	s_bcnt1_i32_b64 s3, s[8:9]
	v_mov_b32_e32 v0, 0x2000
	v_mov_b32_e32 v1, s3
	s_nop 0

.LBB0_797:
	s_or_b64 exec, exec, s[12:13]
	s_and_saveexec_b64 s[12:13], s[16:17]
	s_cbranch_execz .LBB0_799
	v_mov_b32_e32 v2, 1
	global_atomic_add v[0:1], v2, off
	v_mov_b32_e32 v3, 0x2400
	global_atomic_add v3, v2, s[88:89]
	v_mov_b32_e32 v3, 0x2500
	global_atomic_add v3, v2, s[88:89]
	v_mov_b32_e32 v3, 0x2600
	global_atomic_add v3, v2, s[88:89]
	v_mov_b32_e32 v3, 0x2700
	global_atomic_add v3, v2, s[88:89]
	v_mov_b32_e32 v3, 0x2800
	global_atomic_add v3, v2, s[88:89]
	v_mov_b32_e32 v3, 0x2900
	global_atomic_add v3, v2, s[88:89]
	v_mov_b32_e32 v3, 0x2a00
	global_atomic_add v3, v2, s[88:89]
	v_mov_b32_e32 v3, 0x2b00
	global_atomic_add v3, v2, s[88:89]
	v_mov_b32_e32 v3, 0x2c00
	global_atomic_add v3, v2, s[88:89]
	v_mov_b32_e32 v3, 0x2d00
	global_atomic_add v3, v2, s[88:89]
	v_mov_b32_e32 v3, 0x2e00
	global_atomic_add v3, v2, s[88:89]
	v_mov_b32_e32 v3, 0x2f00
	global_atomic_add v3, v2, s[88:89]
	v_mov_b32_e32 v3, 0x3000
	global_atomic_add v3, v2, s[88:89]
	v_mov_b32_e32 v3, 0x3100
	global_atomic_add v3, v2, s[88:89]
	v_mov_b32_e32 v3, 0x3200
	global_atomic_add v3, v2, s[88:89]
	v_mov_b32_e32 v3, 0x3300
	global_atomic_add v3, v2, s[88:89]
.LBB0_799:
	s_or_b64 exec, exec, s[12:13]
	s_mov_b64 s[12:13], exec
	v_mbcnt_lo_u32_b32 v0, s12, 0
	v_mbcnt_hi_u32_b32 v0, s13, v0
	v_cmp_eq_u32_e32 vcc, 0, v0
	s_waitcnt vmcnt(0)
	buffer_inv sc1
	s_and_saveexec_b64 s[14:15], vcc
	s_cbranch_execz .LBB0_801
	s_bcnt1_i32_b64 s3, s[12:13]
	v_mov_b32_e32 v0, 0x2000
	v_mov_b32_e32 v1, s3
	s_nop 0

.LBB0_1025:
	s_or_b64 exec, exec, s[14:15]
	s_and_saveexec_b64 s[14:15], s[18:19]
	s_cbranch_execz .LBB0_1027
	v_mov_b32_e32 v2, 1
	global_atomic_add v[0:1], v2, off
	v_mov_b32_e32 v3, 0x2400
	global_atomic_add v3, v2, s[88:89]
	v_mov_b32_e32 v3, 0x2500
	global_atomic_add v3, v2, s[88:89]
	v_mov_b32_e32 v3, 0x2600
	global_atomic_add v3, v2, s[88:89]
	v_mov_b32_e32 v3, 0x2700
	global_atomic_add v3, v2, s[88:89]
	v_mov_b32_e32 v3, 0x2800
	global_atomic_add v3, v2, s[88:89]
	v_mov_b32_e32 v3, 0x2900
	global_atomic_add v3, v2, s[88:89]
	v_mov_b32_e32 v3, 0x2a00
	global_atomic_add v3, v2, s[88:89]
	v_mov_b32_e32 v3, 0x2b00
	global_atomic_add v3, v2, s[88:89]
	v_mov_b32_e32 v3, 0x2c00
	global_atomic_add v3, v2, s[88:89]
	v_mov_b32_e32 v3, 0x2d00
	global_atomic_add v3, v2, s[88:89]
	v_mov_b32_e32 v3, 0x2e00
	global_atomic_add v3, v2, s[88:89]
	v_mov_b32_e32 v3, 0x2f00
	global_atomic_add v3, v2, s[88:89]
	v_mov_b32_e32 v3, 0x3000
	global_atomic_add v3, v2, s[88:89]
	v_mov_b32_e32 v3, 0x3100
	global_atomic_add v3, v2, s[88:89]
	v_mov_b32_e32 v3, 0x3200
	global_atomic_add v3, v2, s[88:89]
	v_mov_b32_e32 v3, 0x3300
	global_atomic_add v3, v2, s[88:89]
.LBB0_1027:
	s_or_b64 exec, exec, s[14:15]
	s_mov_b64 s[14:15], exec
	v_mbcnt_lo_u32_b32 v0, s14, 0
	v_mbcnt_hi_u32_b32 v0, s15, v0
	v_cmp_eq_u32_e32 vcc, 0, v0
	s_waitcnt vmcnt(0)
	buffer_inv sc1
	s_and_saveexec_b64 s[16:17], vcc
	s_cbranch_execz .LBB0_1029
	s_bcnt1_i32_b64 s3, s[14:15]
	v_mov_b32_e32 v0, 0x2000
	v_mov_b32_e32 v1, s3
	s_nop 0
